# v29 + P13 unit order: the two token-half units that share an A tile are now adjacent as well (8 consecutive units = 4 line-sharing groups x 2 halves)
# speedup vs baseline: 1.0002x; 1.0002x over previous
; #define PG8_STAGE(bufoff, gbase, voff) do { _Pragma("unroll") for (int _i = 0; _i < 2; ++_i) \
;         __builtin_amdgcn_global_load_lds((const unsigned*)((const char*)(gbase) + (voff)[_i]), (PG8_LAS unsigned*)(lds + (bufoff) + ldsw + _i * 8192), 16, 0, 0); } while (0)
; #define PG8_WAIT_V(n) asm volatile("s_waitcnt vmcnt(" #n ")" ::: "memory")
; #define PG8_BAR __builtin_amdgcn_s_barrier()
; template <class Epi, class Sched, bool ALIGN_EPI = false, bool SP2 = false>
; __device__ __forceinline__ void gemm_phase(PG8_LAS unsigned char* lds, const Gemm g, const Sched& S, const Epi& E) {
;     ...
;     const char* cA = (const char*)g.A + (size_t)cur.pm * tstepA; const char* cB = (const char*)g.Bt + (size_t)cur.pn * tstepB;
;     S.a_ready(cur);
;     if constexpr (SP2) {
;         PG8_STAGE(PG8_SB(0, 0), cB, voffB); PG8_STAGE(PG8_SB(0, 1), cB + hstepB, voffB); PG8_STAGE(PG8_SA(0, 0), cA, voffA); PG8_STAGE(PG8_SA(0, 1), cA + hstepA, voffA);
;         if (wr == 1) PG8_BAR;
;         PG8_WAIT_V(2); PG8_BAR;
;         PG8_STAGE(PG8_SB(1, 0), cB + kstep, voffB); PG8_STAGE(PG8_SA(1, 0), cA + kstep, voffA); PG8_STAGE(PG8_SB(1, 1), cB + hstepB + kstep, voffB);
;         PG8_WAIT_V(6); PG8_BAR;
;     } else {
;         PG8_STAGE(PG8_SB(0, 0), cB, voffB); PG8_STAGE(PG8_SA(0, 0), cA, voffA); PG8_STAGE(PG8_SB(0, 1), cB + hstepB, voffB); PG8_STAGE(PG8_SA(0, 1), cA + hstepA, voffA);
;     __device__ bool next(int i, pg8::Unit& u) const { const long L0 = (long)i * G + c; if (L0 >= total) return false;
;         const int L = (int)(L0 % 8) * (total / 8) + (int)(L0 / 8);
;         const int g = L / per, r = L % per;
;         u.pm = g * nMg + r % nMg; u.pn = g * nNg + r / nMg; return true; }
.LBB0_1276:
	s_cmp_gt_i32 s74, 13
	s_cselect_b64 s[0:1], -1, 0
	s_cmp_lt_i32 s75, 14
	s_cselect_b64 s[2:3], -1, 0
	s_or_b64 s[0:1], s[0:1], s[2:3]
	s_and_b64 vcc, exec, s[0:1]
	s_cbranch_vccnz .LBB0_1347
	s_load_dword s22, s[76:77], 0x190
	s_add_u32 s8, s76, 0x190
	s_addc_u32 s9, s77, 0
	s_cmpk_gt_i32 s70, 0x4ff
	v_readfirstlane_b32 s5, v0
	s_cbranch_scc1 .LBB0_1297
	s_waitcnt vmcnt(0)
	v_lshrrev_b32_e32 v1, 5, v0
	v_lshrrev_b32_e32 v12, 1, v0
	v_and_b32_e32 v1, 4, v1
	v_bfe_u32 v2, v0, 2, 2
	v_and_b32_e32 v10, 24, v12
	v_or3_b32 v1, v1, v2, v10
	v_lshlrev_b32_e32 v2, 4, v0
	v_bfe_u32 v3, v0, 3, 25
	v_and_b32_e32 v5, 32, v0
	v_or_b32_e32 v3, 64, v3
	s_movk_i32 s0, 0x60
	v_bitop3_b32 v11, v2, v5, 48 bitop3:0x6c
	v_and_b32_e32 v13, 64, v0
	v_and_or_b32 v4, v3, s0, v1
	v_or_b32_e32 v2, v11, v13
	v_mul_u32_u24_e32 v4, 0x300, v4
	v_lshrrev_b32_e32 v2, 1, v2
	v_or_b32_e32 v4, v4, v2
	v_lshlrev_b32_e32 v130, 1, v4
	v_bfe_u32 v4, v0, 2, 4
	s_movk_i32 s0, 0x70
	s_ashr_i32 s24, s70, 31
	v_and_or_b32 v3, v3, s0, v4
	s_lshr_b32 s0, s24, 29
	s_add_i32 s0, s70, s0
	s_ashr_i32 s0, s0, 3
	s_mul_i32 s1, s70, 0xa0
	s_mulk_i32 s0, 0xfb01
	s_add_i32 s0, s0, s1
	s_mul_hi_i32 s1, s0, 0x66666667
	s_lshr_b32 s2, s1, 31
	s_ashr_i32 s1, s1, 4
	s_add_i32 s1, s1, s2
	s_mul_i32 s2, s1, 40
	s_sub_i32 s0, s0, s2
	s_and_b32 s2, s0, 3
	s_lshl_b32 s1, s1, 2
	s_add_i32 s1, s1, s2
	s_lshr_b32 s0, s0, 2
	s_and_b32 s2, s0, 1
	s_lshr_b32 s0, s0, 1
	s_mul_i32 s2, s2, 5
	s_add_i32 s0, s0, s2
	s_bfe_i32 s3, s0, 0x80000
	s_mulk_i32 s3, 0x67
	s_sext_i32_i16 s7, s3
	s_ashr_i32 s7, s7, 9
	s_bfe_u32 s3, s3, 0x1000f
	s_add_i32 s3, s7, s3
	s_mul_i32 s7, s3, 5
	s_sub_i32 s0, s0, s7
	v_mul_u32_u24_e32 v14, 0x300, v3
	s_mul_i32 s2, s1, 5
	s_sext_i32_i8 s0, s0
	v_or_b32_e32 v3, v14, v2
	s_add_i32 s38, s2, s0
	s_lshl_b32 s0, s1, 1
	s_sext_i32_i16 s1, s3
	s_lshr_b32 s6, s5, 6
	v_lshlrev_b32_e32 v132, 1, v3
	v_lshrrev_b32_e32 v3, 3, v0
	s_add_i32 s39, s0, s1
	s_lshr_b32 s4, s5, 8
	s_lshl_b32 s23, s6, 10
	v_and_or_b32 v1, v3, 32, v1
	s_mul_i32 s1, s39, 0x60000
	v_mul_u32_u24_e32 v1, 0x300, v1
	s_mul_hi_i32 s0, s39, 0x60000
	s_add_u32 s2, s80, s1
	v_or_b32_e32 v1, v1, v2
	s_addc_u32 s3, s81, s0
	s_add_i32 s25, s23, 0
	v_lshlrev_b32_e32 v134, 1, v1
	s_add_i32 m0, s25, 0x10000
	v_and_or_b32 v1, v3, 48, v4
	global_load_lds_dwordx4 v134, s[2:3]
	s_add_i32 m0, s25, 0x12000
	s_add_u32 s0, s2, 0x30000
	global_load_lds_dwordx4 v130, s[2:3]
	s_addc_u32 s1, s3, 0
	s_add_i32 m0, s25, 0x14000
	s_mul_i32 s10, s38, 0x60000
	global_load_lds_dwordx4 v134, s[0:1]
	s_add_i32 m0, s25, 0x16000
	v_mul_u32_u24_e32 v15, 0x300, v1
	s_mul_hi_i32 s7, s38, 0x60000
	global_load_lds_dwordx4 v130, s[0:1]
	s_add_u32 s0, s84, s10
	v_or_b32_e32 v1, v2, v15
	s_addc_u32 s1, s85, s7
	s_add_i32 s26, s25, 0x2000
	v_lshlrev_b32_e32 v136, 1, v1
	s_mov_b32 m0, s25
	s_add_u32 s10, s0, 0x30000
	global_load_lds_dwordx4 v136, s[0:1]
	s_mov_b32 m0, s26
	s_addc_u32 s11, s1, 0
	s_add_i32 s27, s25, 0x4000
	global_load_lds_dwordx4 v132, s[0:1]
	s_mov_b32 m0, s27
	s_add_i32 s28, s25, 0x6000
	global_load_lds_dwordx4 v136, s[10:11]
	s_mov_b32 m0, s28
	v_mov_b32_e32 v139, 0
	global_load_lds_dwordx4 v132, s[10:11]
	v_mov_b32_e32 v135, v139
	v_mov_b32_e32 v131, v139
	v_mov_b32_e32 v137, v139
	v_mov_b32_e32 v133, v139
	s_cmp_eq_u32 s4, 1
	s_mov_b32 s29, 0
	v_lshl_add_u64 v[8:9], s[2:3], 0, v[134:135]
	v_lshl_add_u64 v[6:7], s[2:3], 0, v[130:131]
	v_lshl_add_u64 v[2:3], s[0:1], 0, v[136:137]
	s_cselect_b64 s[10:11], -1, 0
	s_cmp_lg_u32 s4, 1
	v_lshl_add_u64 v[4:5], s[0:1], 0, v[132:133]
	s_cbranch_scc1 .LBB0_1280
	s_barrier

; template <class Epi, class Sched, bool ALIGN_EPI = false, bool SP2 = false>
; __device__ __forceinline__ void gemm_phase(PG8_LAS unsigned char* lds, const Gemm g, const Sched& S, const Epi& E) {
;     ...
;         const bool has_next = S.next(ui + 1, nxt);
;         const char* nA = has_next ? (const char*)g.A + (size_t)nxt.pm * tstepA : cA; const char* nB = has_next ? (const char*)g.Bt + (size_t)nxt.pn * tstepB : cB;
;     __device__ bool next(int i, pg8::Unit& u) const { const long L0 = (long)i * G + c; if (L0 >= total) return false;
;         const int L = (int)(L0 % 8) * (total / 8) + (int)(L0 / 8);
;         const int g = L / per, r = L % per;
;         u.pm = g * nMg + r % nMg; u.pn = g * nNg + r / nMg; return true; }
.LBB0_1283:
	s_add_i32 s29, s29, 1
	s_mul_i32 s4, s29, s33
	s_mul_hi_u32 s5, s29, s22
	s_add_i32 s5, s5, s4
	s_mul_i32 s4, s29, s22
	s_add_u32 s4, s4, s70
	s_addc_u32 s5, s5, s24
	v_cmp_gt_i64_e32 vcc, s[4:5], v[146:147]
	v_cmp_lt_i64_e64 s[6:7], s[4:5], v[144:145]
	s_cbranch_vccnz .LBB0_1285
	s_ashr_i32 s16, s5, 31
	s_lshr_b32 s16, s16, 29
	s_add_u32 s16, s4, s16
	s_addc_u32 s17, s5, 0
	s_lshr_b64 s[16:17], s[16:17], 3
	s_lshl_b32 s5, s16, 3
	s_sub_i32 s4, s4, s5
	s_mulk_i32 s4, 0xa0
	s_add_i32 s4, s4, s16
	s_mul_hi_i32 s5, s4, 0x66666667
	s_lshr_b32 s16, s5, 31
	s_ashr_i32 s5, s5, 4
	s_add_i32 s5, s5, s16
	s_mul_i32 s16, s5, 40
	s_sub_i32 s4, s4, s16
	s_and_b32 s16, s4, 3
	s_lshl_b32 s5, s5, 2
	s_add_i32 s5, s5, s16
	s_lshr_b32 s4, s4, 2
	s_and_b32 s16, s4, 1
	s_lshr_b32 s4, s4, 1
	s_mul_i32 s16, s16, 5
	s_add_i32 s4, s4, s16
	s_mul_i32 s17, s4, 0x67
	s_sext_i32_i16 s20, s17
	s_ashr_i32 s20, s20, 9
	s_bfe_u32 s17, s17, 0x1000f
	s_add_i32 s17, s20, s17
	s_mul_i32 s20, s17, 5
	s_sub_i32 s4, s4, s20
	s_mul_i32 s16, s5, 5
	s_sext_i32_i8 s4, s4
	s_add_i32 s36, s16, s4
	s_lshl_b32 s4, s5, 1
	s_sext_i32_i16 s5, s17
	s_add_i32 s37, s4, s5
